# as v42 plus down-GEMM EpiRes: first 5 residual quads loaded into K-loop-free VGPRs before the K-loop (hidden under it), copied at epilogue start; remaining 11 loads covered by processing the first qua
# baseline (speedup 1.0000x reference)
; template <class Epi, bool ALIGN_EPI>
; __device__ __forceinline__ void gemm_phase(LAS unsigned char* lds, const Gemm g, const StaticOrder S, const Epi E) {
;     ...
; #pragma unroll
;         for (int a = 0; a < 2; ++a)
; #pragma unroll
;             for (int b = 0; b < 2; ++b)
; #pragma unroll
;                 for (int m = 0; m < 4; ++m)
; #pragma unroll
;                     for (int n = 0; n < 2; ++n) acc[a][b][m][n] = (f32x4){0.f, 0.f, 0.f, 0.f};
;     __device__ __forceinline__ void operator()(const f32x4 (&acc)[2][2][4][2], const Unit& u, int wr, int wc, int fr, int fq, const float (&rs)[2][4]) const {
;     ...
;             for (int m = 0; m < 4; ++m) { bf16_t* rowp = X + (size_t)(row0 + ai * HALF + m * 16) * DM + col0; float ss = 0.f;
; #pragma unroll
;                 for (int bj = 0; bj < 2; ++bj) { const u32x4 bw = *(const u32x4*)(rowp + bj * HALF); const f32x4 a0 = acc[ai][bj][m][0], a1 = acc[ai][bj][m][1];
.LBB0_727:
	s_add_u32 s28, s50, 0x100
	v_mov_b32_e32 v0, 0
	s_addc_u32 s29, s51, 0
	s_mov_b32 s30, -2
	v_mov_b32_e32 v1, 0
	v_mov_b64_e32 v[2:3], 0
	v_mov_b64_e32 v[4:5], 0
	v_mov_b64_e32 v[6:7], 0
	v_mov_b64_e32 v[8:9], 0
	v_mov_b64_e32 v[10:11], 0
	v_mov_b64_e32 v[12:13], 0
	v_mov_b64_e32 v[14:15], 0
	v_mov_b64_e32 v[16:17], 0
	v_mov_b64_e32 v[18:19], 0
	v_mov_b64_e32 v[20:21], 0
	v_mov_b64_e32 v[22:23], 0
	v_mov_b64_e32 v[24:25], 0
	v_mov_b64_e32 v[26:27], 0
	v_mov_b64_e32 v[28:29], 0
	v_mov_b64_e32 v[30:31], 0
	v_mov_b64_e32 v[32:33], 0
	v_mov_b64_e32 v[34:35], 0
	v_mov_b64_e32 v[36:37], 0
	v_mov_b64_e32 v[38:39], 0
	v_mov_b64_e32 v[40:41], 0
	v_mov_b64_e32 v[42:43], 0
	v_mov_b64_e32 v[44:45], 0
	v_mov_b64_e32 v[46:47], 0
	v_mov_b64_e32 v[48:49], 0
	v_mov_b64_e32 v[50:51], 0
	v_mov_b64_e32 v[52:53], 0
	v_mov_b64_e32 v[54:55], 0
	v_mov_b64_e32 v[56:57], 0
	v_mov_b64_e32 v[58:59], 0
	v_mov_b64_e32 v[60:61], 0
	v_mov_b64_e32 v[62:63], 0
	v_mov_b64_e32 v[64:65], 0
	v_mov_b64_e32 v[66:67], 0
	v_mov_b64_e32 v[68:69], 0
	v_mov_b64_e32 v[70:71], 0
	v_mov_b64_e32 v[72:73], 0
	v_mov_b64_e32 v[74:75], 0
	v_mov_b64_e32 v[76:77], 0
	v_mov_b64_e32 v[78:79], 0
	v_mov_b64_e32 v[82:83], 0
	v_mov_b64_e32 v[84:85], 0
	v_mov_b64_e32 v[86:87], 0
	v_mov_b64_e32 v[88:89], 0
	v_mov_b64_e32 v[90:91], 0
	v_mov_b64_e32 v[92:93], 0
	v_mov_b64_e32 v[94:95], 0
	v_mov_b64_e32 v[96:97], 0
	v_mov_b64_e32 v[98:99], 0
	v_mov_b64_e32 v[100:101], 0
	v_mov_b64_e32 v[102:103], 0
	v_mov_b64_e32 v[104:105], 0
	v_mov_b64_e32 v[106:107], 0
	v_mov_b64_e32 v[108:109], 0
	v_mov_b64_e32 v[110:111], 0
	v_mov_b64_e32 v[112:113], 0
	v_mov_b64_e32 v[114:115], 0
	v_mov_b64_e32 v[116:117], 0
	v_mov_b64_e32 v[118:119], 0
	v_mov_b64_e32 v[120:121], 0
	v_mov_b64_e32 v[122:123], 0
	v_mov_b64_e32 v[124:125], 0
	v_mov_b64_e32 v[126:127], 0
	v_mov_b64_e32 v[128:129], 0
	s_lshl_b32 s0, s27, 8
	s_add_i32 s0, s0, s71
	v_add_u32_e32 v250, s0, v151
	s_lshl_b32 s0, s26, 8
	s_or_b32 s0, s0, s72
	v_ashrrev_i32_e32 v251, 31, v250
	v_lshl_add_u32 v134, v150, 3, s0
	v_lshlrev_b64 v[250:251], 11, v[250:251]
	v_ashrrev_i32_e32 v135, 31, v134
	v_lshl_add_u64 v[250:251], s[94:95], 0, v[250:251]
	v_lshl_add_u64 v[250:251], v[134:135], 1, v[250:251]
	global_load_dwordx4 v[230:233], v[250:251], off
	global_load_dwordx4 v[234:237], v[250:251], off offset:256
	s_mov_b32 s0, 0x8000
	s_mov_b32 s1, 0
	v_lshl_add_u64 v[134:135], v[250:251], 0, s[0:1]
	global_load_dwordx4 v[238:241], v[134:135], off
	global_load_dwordx4 v[242:245], v[134:135], off offset:256
	s_mov_b32 s0, 0x10000
	v_lshl_add_u64 v[250:251], v[250:251], 0, s[0:1]
	global_load_dwordx4 v[246:249], v[250:251], off
	v_readfirstlane_b32 s0, v167
	s_nop 3
	s_cmpk_lt_u32 s0, 0x100
	s_cbranch_scc1 .Lprio_k1
	s_setprio 1

; __device__ __forceinline__ unsigned cvt_pk_bf16(float lo, float hi) { unsigned r; asm volatile("v_cvt_pk_bf16_f32 %0, %1, %2" : "=v"(r) : "v"(lo), "v"(hi)); return r; }
; __device__ __forceinline__ float bf_lo(unsigned w) { return __uint_as_float(w << 16); }
; __device__ __forceinline__ float bf_hi(unsigned w) { return __uint_as_float(w & 0xffff0000u); }
;     __device__ __forceinline__ void operator()(const f32x4 (&acc)[2][2][4][2], const Unit& u, int wr, int wc, int fr, int fq, const float (&rs)[2][4]) const {
;     ...
;         const int row0 = u.pm * BM + wr * 64 + fr, col0 = u.pn * BM + wc * 32 + 8 * fq;
; #pragma unroll
;         for (int ai = 0; ai < 2; ++ai) {
; #pragma unroll
;             for (int m = 0; m < 4; ++m) { bf16_t* rowp = X + (size_t)(row0 + ai * HALF + m * 16) * DM + col0; float ss = 0.f;
; #pragma unroll
;                 for (int bj = 0; bj < 2; ++bj) { const u32x4 bw = *(const u32x4*)(rowp + bj * HALF); const f32x4 a0 = acc[ai][bj][m][0], a1 = acc[ai][bj][m][1];
;                     u32x4 w; w.x = cvt_pk_bf16(bf_lo(bw.x) + alpha * a0[0], bf_hi(bw.x) + alpha * a0[1]); w.y = cvt_pk_bf16(bf_lo(bw.y) + alpha * a0[2], bf_hi(bw.y) + alpha * a0[3]);
;                     w.z = cvt_pk_bf16(bf_lo(bw.z) + alpha * a1[0], bf_hi(bw.z) + alpha * a1[1]); w.w = cvt_pk_bf16(bf_lo(bw.w) + alpha * a1[2], bf_hi(bw.w) + alpha * a1[3]);
;                     *(u32x4*)(rowp + bj * HALF) = w;
;                     ss += (bf_lo(w.x) * bf_lo(w.x) + bf_hi(w.x) * bf_hi(w.x)) + (bf_lo(w.y) * bf_lo(w.y) + bf_hi(w.y) * bf_hi(w.y));
;                     ss += (bf_lo(w.z) * bf_lo(w.z) + bf_hi(w.z) * bf_hi(w.z)) + (bf_lo(w.w) * bf_lo(w.w) + bf_hi(w.w) * bf_hi(w.w)); }
;                 ss = fq_sum(ss);
;                 if (fq == 0) part[(size_t)(row0 + ai * HALF + m * 16) * 16 + u.pn * 4 + wc] = ss; } }
.LBB0_731:
	v_mov_b64_e32 v[182:183], v[230:231]
	v_mov_b64_e32 v[184:185], v[232:233]
	v_mov_b64_e32 v[186:187], v[234:235]
	v_mov_b64_e32 v[188:189], v[236:237]
	v_mov_b64_e32 v[190:191], v[238:239]
	v_mov_b64_e32 v[192:193], v[240:241]
	v_mov_b64_e32 v[194:195], v[242:243]
	v_mov_b64_e32 v[196:197], v[244:245]
	v_mov_b64_e32 v[198:199], v[246:247]
	v_mov_b64_e32 v[200:201], v[248:249]
	s_lshl_b32 s0, s27, 8
	v_mov_b32_e32 v130, v151
	v_mov_b32_e32 v131, v150
	s_add_i32 s0, s0, s71
	s_lshl_b32 s48, s26, 2
	v_add_u32_e32 v148, s0, v130
	s_lshl_b32 s0, s26, 8
	s_or_b32 s0, s0, s72
	v_ashrrev_i32_e32 v149, 31, v148
	v_lshl_add_u32 v146, v131, 3, s0
	v_lshlrev_b64 v[154:155], 11, v[148:149]
	v_ashrrev_i32_e32 v147, 31, v146
	v_lshl_add_u64 v[154:155], s[94:95], 0, v[154:155]
	v_lshl_add_u64 v[158:159], v[146:147], 1, v[154:155]
	v_add_u32_e32 v246, 16, v148
	v_ashrrev_i32_e32 v247, 31, v246
	v_lshlrev_b64 v[246:247], 11, v[246:247]
	v_lshl_add_u64 v[246:247], s[94:95], 0, v[246:247]
	v_lshl_add_u64 v[246:247], v[146:147], 1, v[246:247]
	v_add_u32_e32 v248, 32, v148
	v_ashrrev_i32_e32 v249, 31, v248
	v_lshlrev_b64 v[248:249], 11, v[248:249]
	v_lshl_add_u64 v[248:249], s[94:95], 0, v[248:249]
	v_lshl_add_u64 v[248:249], v[146:147], 1, v[248:249]
	global_load_dwordx4 v[202:205], v[248:249], off offset:256
	v_add_u32_e32 v246, 48, v148
	v_ashrrev_i32_e32 v247, 31, v246
	v_lshlrev_b64 v[246:247], 11, v[246:247]
	v_lshl_add_u64 v[246:247], s[94:95], 0, v[246:247]
	v_lshl_add_u64 v[246:247], v[146:147], 1, v[246:247]
	global_load_dwordx4 v[206:209], v[246:247], off
	global_load_dwordx4 v[210:213], v[246:247], off offset:256
	v_add_u32_e32 v248, 0x80, v148
	v_ashrrev_i32_e32 v249, 31, v248
	v_lshlrev_b64 v[248:249], 11, v[248:249]
	v_lshl_add_u64 v[248:249], s[94:95], 0, v[248:249]
	v_lshl_add_u64 v[248:249], v[146:147], 1, v[248:249]
	global_load_dwordx4 v[214:217], v[248:249], off
	global_load_dwordx4 v[218:221], v[248:249], off offset:256
	v_add_u32_e32 v246, 0x90, v148
	v_ashrrev_i32_e32 v247, 31, v246
	v_lshlrev_b64 v[246:247], 11, v[246:247]
	v_lshl_add_u64 v[246:247], s[94:95], 0, v[246:247]
	v_lshl_add_u64 v[246:247], v[146:147], 1, v[246:247]
	global_load_dwordx4 v[222:225], v[246:247], off
	global_load_dwordx4 v[226:229], v[246:247], off offset:256
	v_add_u32_e32 v248, 0xa0, v148
	v_ashrrev_i32_e32 v249, 31, v248
	v_lshlrev_b64 v[248:249], 11, v[248:249]
	v_lshl_add_u64 v[248:249], s[94:95], 0, v[248:249]
	v_lshl_add_u64 v[248:249], v[146:147], 1, v[248:249]
	global_load_dwordx4 v[230:233], v[248:249], off
	global_load_dwordx4 v[234:237], v[248:249], off offset:256
	v_add_u32_e32 v246, 0xb0, v148
	v_ashrrev_i32_e32 v247, 31, v246
	v_lshlrev_b64 v[246:247], 11, v[246:247]
	v_lshl_add_u64 v[246:247], s[94:95], 0, v[246:247]
	v_lshl_add_u64 v[246:247], v[146:147], 1, v[246:247]
	global_load_dwordx4 v[238:241], v[246:247], off
	global_load_dwordx4 v[242:245], v[246:247], off offset:256
	s_ashr_i32 s49, s48, 31
	v_cmp_eq_u32_e32 vcc, 0, v131
	s_waitcnt vmcnt(15)
	v_lshlrev_b32_e32 v130, 16, v182
	v_and_b32_e32 v134, 0xffff0000, v182
	v_lshlrev_b32_e32 v135, 16, v183
	v_and_b32_e32 v154, 0xffff0000, v183
	v_lshlrev_b32_e32 v155, 16, v184
	v_and_b32_e32 v156, 0xffff0000, v184
	v_lshlrev_b32_e32 v160, 16, v185
	v_and_b32_e32 v157, 0xffff0000, v185
	v_fmac_f32_e32 v130, 0.5, v126
	v_fmac_f32_e32 v134, 0.5, v127
	v_fmac_f32_e32 v135, 0.5, v128
	v_fmac_f32_e32 v154, 0.5, v129
	v_fmac_f32_e32 v155, 0.5, v122
	v_fmac_f32_e32 v156, 0.5, v123
	v_fmac_f32_e32 v160, 0.5, v124
	v_fmac_f32_e32 v157, 0.5, v125
	v_cvt_pk_bf16_f32 v122, v130, v134
	v_cvt_pk_bf16_f32 v123, v135, v154
	v_cvt_pk_bf16_f32 v124, v155, v156
	v_cvt_pk_bf16_f32 v125, v160, v157
	s_nop 0
	v_lshlrev_b32_e32 v130, 16, v122
	global_store_dwordx4 v[158:159], v[122:125], off
	v_lshlrev_b32_e32 v134, 16, v123
	v_lshlrev_b32_e32 v135, 16, v124
	v_and_b32_e32 v122, 0xffff0000, v122
	v_and_b32_e32 v123, 0xffff0000, v123
	v_and_b32_e32 v124, 0xffff0000, v124
	v_lshlrev_b32_e32 v154, 16, v125
	v_and_b32_e32 v125, 0xffff0000, v125
	v_mul_f32_e32 v122, v122, v122
	v_mul_f32_e32 v123, v123, v123
	v_mul_f32_e32 v124, v124, v124
	v_mul_f32_e32 v125, v125, v125
	v_fmac_f32_e32 v122, v130, v130
	v_fmac_f32_e32 v123, v134, v134
	v_fmac_f32_e32 v124, v135, v135
	v_fmac_f32_e32 v125, v154, v154
	v_add_f32_e32 v122, v122, v123
	v_add_f32_e32 v123, v124, v125
	v_add_f32_e32 v122, v122, v123
	s_waitcnt vmcnt(15)
	v_lshlrev_b32_e32 v123, 16, v186
	v_and_b32_e32 v124, 0xffff0000, v186
	v_lshlrev_b32_e32 v125, 16, v187
	v_and_b32_e32 v126, 0xffff0000, v187
	v_lshlrev_b32_e32 v127, 16, v188
	v_and_b32_e32 v128, 0xffff0000, v188
	v_lshlrev_b32_e32 v130, 16, v189
	v_and_b32_e32 v129, 0xffff0000, v189
	v_fmac_f32_e32 v123, 0.5, v118
	v_fmac_f32_e32 v124, 0.5, v119
	v_fmac_f32_e32 v125, 0.5, v120
	v_fmac_f32_e32 v126, 0.5, v121
	v_fmac_f32_e32 v127, 0.5, v114
	v_fmac_f32_e32 v128, 0.5, v115
	v_cvt_pk_bf16_f32 v114, v123, v124
	v_cvt_pk_bf16_f32 v115, v125, v126
	v_fmac_f32_e32 v130, 0.5, v116
	v_and_b32_e32 v119, 0xffff0000, v114
	v_and_b32_e32 v121, 0xffff0000, v115
	v_fmac_f32_e32 v129, 0.5, v117
	v_cvt_pk_bf16_f32 v116, v127, v128
	v_cvt_pk_bf16_f32 v117, v130, v129
	v_lshlrev_b32_e32 v118, 16, v114
	v_lshlrev_b32_e32 v120, 16, v115
	v_and_b32_e32 v124, 0xffff0000, v116
	v_and_b32_e32 v126, 0xffff0000, v117
	v_mul_f32_e32 v119, v119, v119
	v_mul_f32_e32 v121, v121, v121
	v_lshlrev_b32_e32 v123, 16, v116
	v_lshlrev_b32_e32 v125, 16, v117
	v_mul_f32_e32 v124, v124, v124
	v_mul_f32_e32 v126, v126, v126
	v_fmac_f32_e32 v119, v118, v118
	v_fmac_f32_e32 v121, v120, v120
	v_fmac_f32_e32 v124, v123, v123
	v_fmac_f32_e32 v126, v125, v125
	v_add_f32_e32 v118, v119, v121
	v_add_f32_e32 v119, v124, v126
	v_add_f32_e32 v118, v122, v118
	v_add_f32_e32 v118, v118, v119
	ds_swizzle_b32 v119, v118 offset:swizzle(SWAP,16)
	global_store_dwordx4 v[158:159], v[114:117], off offset:256
	s_waitcnt lgkmcnt(0)
	s_nop 0
	v_add_f32_e32 v114, v118, v119
	v_mov_b32_e32 v115, v114
	s_nop 1
	v_permlane32_swap_b32_e32 v114, v115
	s_and_saveexec_b64 s[50:51], vcc
	s_cbranch_execz .LBB0_733
	v_lshlrev_b64 v[116:117], 6, v[148:149]
	v_lshl_add_u64 v[116:117], s[96:97], 0, v[116:117]
	v_lshl_add_u64 v[116:117], s[48:49], 2, v[116:117]
	s_lshl_b32 s58, s70, 2
	v_lshl_add_u64 v[116:117], v[116:117], 0, s[58:59]
	v_add_f32_e32 v114, v114, v115
	global_store_dword v[116:117], v114, off
